# phase 11: the four K=512 branch GEMMs of a tile keep their accumulators in registers (per-row rescale by the ratio of the branches' RMS factors between calls); only the last call runs the gate + read-
# speedup vs baseline: 1.0323x; 1.0323x over previous
.LBB0_401:
	s_ashr_i32 s27, s26, 31
	s_lshl_b64 s[30:31], s[26:27], 19
	s_add_u32 s30, s12, s30
	s_addc_u32 s31, s13, s31
	s_and_b64 s[0:1], s[0:1], exec
	s_cselect_b32 s27, s31, s35
	s_cselect_b32 s52, s30, s34
	s_add_u32 s0, s34, 0x40080
	s_addc_u32 s1, s35, 0
	s_add_u32 s34, s8, 0x100
	s_addc_u32 s35, s9, 0
	s_mov_b32 s8, 0
	s_and_b64 vcc, exec, s[2:3]
	s_cbranch_vccz .Lfuse_zero
	s_cmp_eq_u32 s4, 0
	s_cbranch_scc1 .Lfuse_zero
	v_mov_b32_e32 v2, v206
	v_mov_b32_e32 v3, v207
	v_mov_b32_e32 v4, v208
	v_mov_b32_e32 v5, v209
	v_mov_b32_e32 v6, v210
	v_mov_b32_e32 v7, v211
	v_mov_b32_e32 v8, v212
	v_mov_b32_e32 v9, v213
	v_mov_b32_e32 v10, v214
	v_mov_b32_e32 v11, v215
	v_mov_b32_e32 v12, v226
	v_mov_b32_e32 v13, v227
	v_mov_b32_e32 v14, v228
	v_mov_b32_e32 v15, v229
	v_mov_b32_e32 v16, v230
	v_mov_b32_e32 v17, v231
	v_mov_b32_e32 v18, v232
	v_mov_b32_e32 v19, v233
	s_waitcnt vmcnt(0)
	s_branch .Lfuse_keep
.Lfuse_zero:
	v_mov_b32_e32 v2, 0
	v_mov_b32_e32 v3, v2
	v_mov_b32_e32 v4, v2
	v_mov_b32_e32 v5, v2
	v_mov_b32_e32 v6, v2
	v_mov_b32_e32 v7, v2
	v_mov_b32_e32 v8, v2
	v_mov_b32_e32 v9, v2
	v_mov_b32_e32 v18, v2
	v_mov_b32_e32 v19, v2
	v_mov_b32_e32 v20, v2
	v_mov_b32_e32 v21, v2
	v_mov_b32_e32 v22, v2
	v_mov_b32_e32 v23, v2
	v_mov_b32_e32 v24, v2
	v_mov_b32_e32 v25, v2
	v_mov_b32_e32 v34, v2
	v_mov_b32_e32 v35, v2
	v_mov_b32_e32 v36, v2
	v_mov_b32_e32 v37, v2
	v_mov_b32_e32 v38, v2
	v_mov_b32_e32 v39, v2
	v_mov_b32_e32 v40, v2
	v_mov_b32_e32 v41, v2
	v_mov_b32_e32 v50, v2
	v_mov_b32_e32 v51, v2
	v_mov_b32_e32 v52, v2
	v_mov_b32_e32 v53, v2
	v_mov_b32_e32 v54, v2
	v_mov_b32_e32 v55, v2
	v_mov_b32_e32 v56, v2
	v_mov_b32_e32 v57, v2
	v_mov_b32_e32 v10, v2
	v_mov_b32_e32 v11, v2
	v_mov_b32_e32 v12, v2
	v_mov_b32_e32 v13, v2
	v_mov_b32_e32 v14, v2
	v_mov_b32_e32 v15, v2
	v_mov_b32_e32 v16, v2
	v_mov_b32_e32 v17, v2
	v_mov_b32_e32 v26, v2
	v_mov_b32_e32 v27, v2
	v_mov_b32_e32 v28, v2
	v_mov_b32_e32 v29, v2
	v_mov_b32_e32 v30, v2
	v_mov_b32_e32 v31, v2
	v_mov_b32_e32 v32, v2
	v_mov_b32_e32 v33, v2
	v_mov_b32_e32 v42, v2
	v_mov_b32_e32 v43, v2
	v_mov_b32_e32 v44, v2
	v_mov_b32_e32 v45, v2
	v_mov_b32_e32 v46, v2
	v_mov_b32_e32 v47, v2
	v_mov_b32_e32 v48, v2
	v_mov_b32_e32 v49, v2
	v_mov_b32_e32 v58, v2
	v_mov_b32_e32 v59, v2
	v_mov_b32_e32 v60, v2
	v_mov_b32_e32 v61, v2
	v_mov_b32_e32 v62, v2
	v_mov_b32_e32 v63, v2
	v_mov_b32_e32 v64, v2
	v_mov_b32_e32 v65, v2
	v_mov_b32_e32 v66, v2
	v_mov_b32_e32 v67, v2
	v_mov_b32_e32 v68, v2
	v_mov_b32_e32 v69, v2
	v_mov_b32_e32 v70, v2
	v_mov_b32_e32 v71, v2
	v_mov_b32_e32 v72, v2
	v_mov_b32_e32 v73, v2
	v_mov_b32_e32 v82, v2
	v_mov_b32_e32 v83, v2
	v_mov_b32_e32 v84, v2
	v_mov_b32_e32 v85, v2
	v_mov_b32_e32 v86, v2
	v_mov_b32_e32 v87, v2
	v_mov_b32_e32 v88, v2
	v_mov_b32_e32 v89, v2
	v_mov_b32_e32 v98, v2
	v_mov_b32_e32 v99, v2
	v_mov_b32_e32 v100, v2
	v_mov_b32_e32 v101, v2
	v_mov_b32_e32 v102, v2
	v_mov_b32_e32 v103, v2
	v_mov_b32_e32 v104, v2
	v_mov_b32_e32 v105, v2
	v_mov_b32_e32 v114, v2
	v_mov_b32_e32 v115, v2
	v_mov_b32_e32 v116, v2
	v_mov_b32_e32 v117, v2
	v_mov_b32_e32 v118, v2
	v_mov_b32_e32 v119, v2
	v_mov_b32_e32 v120, v2
	v_mov_b32_e32 v121, v2
	v_mov_b32_e32 v74, v2
	v_mov_b32_e32 v75, v2
	v_mov_b32_e32 v76, v2
	v_mov_b32_e32 v77, v2
	v_mov_b32_e32 v78, v2
	v_mov_b32_e32 v79, v2
	v_mov_b32_e32 v80, v2
	v_mov_b32_e32 v81, v2
	v_mov_b32_e32 v90, v2
	v_mov_b32_e32 v91, v2
	v_mov_b32_e32 v92, v2
	v_mov_b32_e32 v93, v2
	v_mov_b32_e32 v94, v2
	v_mov_b32_e32 v95, v2
	v_mov_b32_e32 v96, v2
	v_mov_b32_e32 v97, v2
	v_mov_b32_e32 v106, v2
	v_mov_b32_e32 v107, v2
	v_mov_b32_e32 v108, v2
	v_mov_b32_e32 v109, v2
	v_mov_b32_e32 v110, v2
	v_mov_b32_e32 v111, v2
	v_mov_b32_e32 v112, v2
	v_mov_b32_e32 v113, v2
	v_mov_b32_e32 v122, v2
	v_mov_b32_e32 v123, v2
	s_waitcnt vmcnt(0)
	v_mov_b32_e32 v124, v2
	v_mov_b32_e32 v125, v2
	v_mov_b32_e32 v126, v2
	v_mov_b32_e32 v127, v2
	v_mov_b32_e32 v128, v2
	v_mov_b32_e32 v129, v2
.Lfuse_keep:
.LBB0_402:
	s_add_i32 s53, s8, 2
	s_add_u32 s54, s0, 0xfffc0080
	s_addc_u32 s9, s1, -1
	s_add_i32 s56, 0, 0x10000
	s_cmp_eq_u32 s47, s8
	s_cselect_b32 s9, s27, s9
	s_cselect_b32 s8, s52, s54
	v_add_u32_e32 v0, s56, v141
	s_cselect_b32 s55, s29, s35
	s_cselect_b32 s54, s28, s34
	s_add_i32 s57, 0, 0x14000
	ds_read_b128 v[148:151], v0
	ds_read_b128 v[152:155], v0 offset:1024
	ds_read_b128 v[156:159], v0 offset:2048
	ds_read_b128 v[164:167], v0 offset:3072
	v_add_u32_e32 v0, s57, v141
	ds_read_b128 v[168:171], v0
	ds_read_b128 v[172:175], v0 offset:1024
	ds_read_b128 v[176:179], v0 offset:2048
	ds_read_b128 v[180:183], v0 offset:3072
	v_lshl_add_u64 v[226:227], s[0:1], 0, v[142:143]
	s_add_i32 m0, s40, 0xc000
	ds_read_b128 v[184:187], v147
	ds_read_b128 v[188:191], v147 offset:1024
	ds_read_b128 v[192:195], v147 offset:2048
	ds_read_b128 v[196:199], v147 offset:3072
	ds_read_b128 v[200:203], v147 offset:4096
	ds_read_b128 v[204:207], v147 offset:5120
	ds_read_b128 v[208:211], v147 offset:6144
	ds_read_b128 v[212:215], v147 offset:7168
	global_load_lds_dwordx4 v[226:227], off
	v_lshl_add_u64 v[226:227], s[0:1], 0, v[144:145]
	s_add_i32 m0, s40, 0xe000
	s_nop 0
	global_load_lds_dwordx4 v[226:227], off
	s_waitcnt vmcnt(8)
	s_waitcnt lgkmcnt(0)
	s_barrier
	s_setprio 1
	s_waitcnt lgkmcnt(0)
	v_mfma_f32_16x16x32_bf16 v[126:129], v[148:151], v[184:187], v[126:129]
	v_mfma_f32_16x16x32_bf16 v[122:125], v[156:159], v[184:187], v[122:125]
	v_mfma_f32_16x16x32_bf16 v[110:113], v[148:151], v[192:195], v[110:113]
	v_mfma_f32_16x16x32_bf16 v[106:109], v[156:159], v[192:195], v[106:109]
	v_mfma_f32_16x16x32_bf16 v[94:97], v[148:151], v[200:203], v[94:97]
	v_mfma_f32_16x16x32_bf16 v[90:93], v[156:159], v[200:203], v[90:93]
	v_mfma_f32_16x16x32_bf16 v[78:81], v[148:151], v[208:211], v[78:81]
	v_mfma_f32_16x16x32_bf16 v[74:77], v[156:159], v[208:211], v[74:77]
	v_mfma_f32_16x16x32_bf16 v[126:129], v[152:155], v[188:191], v[126:129]
	v_mfma_f32_16x16x32_bf16 v[122:125], v[164:167], v[188:191], v[122:125]
	v_mfma_f32_16x16x32_bf16 v[110:113], v[152:155], v[196:199], v[110:113]
	v_mfma_f32_16x16x32_bf16 v[106:109], v[164:167], v[196:199], v[106:109]
	v_mfma_f32_16x16x32_bf16 v[94:97], v[152:155], v[204:207], v[94:97]
	v_mfma_f32_16x16x32_bf16 v[90:93], v[164:167], v[204:207], v[90:93]
	v_mfma_f32_16x16x32_bf16 v[78:81], v[152:155], v[212:215], v[78:81]
	v_mfma_f32_16x16x32_bf16 v[74:77], v[164:167], v[212:215], v[74:77]
	s_setprio 0
	s_setprio 1
	v_mfma_f32_16x16x32_bf16 v[118:121], v[168:171], v[184:187], v[118:121]
	v_mfma_f32_16x16x32_bf16 v[114:117], v[176:179], v[184:187], v[114:117]
	v_mfma_f32_16x16x32_bf16 v[102:105], v[168:171], v[192:195], v[102:105]
	v_mfma_f32_16x16x32_bf16 v[98:101], v[176:179], v[192:195], v[98:101]
	v_mfma_f32_16x16x32_bf16 v[86:89], v[168:171], v[200:203], v[86:89]
	v_mfma_f32_16x16x32_bf16 v[82:85], v[176:179], v[200:203], v[82:85]
	v_mfma_f32_16x16x32_bf16 v[70:73], v[168:171], v[208:211], v[70:73]
	v_mfma_f32_16x16x32_bf16 v[66:69], v[176:179], v[208:211], v[66:69]
	v_mfma_f32_16x16x32_bf16 v[118:121], v[172:175], v[188:191], v[118:121]
	v_mfma_f32_16x16x32_bf16 v[114:117], v[180:183], v[188:191], v[114:117]
	v_mfma_f32_16x16x32_bf16 v[102:105], v[172:175], v[196:199], v[102:105]
	v_mfma_f32_16x16x32_bf16 v[98:101], v[180:183], v[196:199], v[98:101]
	v_mfma_f32_16x16x32_bf16 v[86:89], v[172:175], v[204:207], v[86:89]
	v_mfma_f32_16x16x32_bf16 v[82:85], v[180:183], v[204:207], v[82:85]
	v_mfma_f32_16x16x32_bf16 v[70:73], v[172:175], v[212:215], v[70:73]
	v_mfma_f32_16x16x32_bf16 v[66:69], v[180:183], v[212:215], v[66:69]
	s_setprio 0
	s_barrier
	s_add_i32 s56, s56, s39
	v_lshl_add_u64 v[226:227], s[54:55], 0, v[134:135]
	s_mov_b32 m0, s56
	ds_read_b128 v[184:187], v147 offset:16384
	ds_read_b128 v[188:191], v147 offset:17408
	ds_read_b128 v[192:195], v147 offset:18432
	ds_read_b128 v[196:199], v147 offset:19456
	ds_read_b128 v[200:203], v147 offset:20480
	ds_read_b128 v[204:207], v147 offset:21504
	ds_read_b128 v[208:211], v147 offset:22528
	ds_read_b128 v[212:215], v147 offset:23552
	global_load_lds_dwordx4 v[226:227], off
	s_add_i32 m0, s56, 0x2000
	v_lshl_add_u64 v[228:229], s[54:55], 0, v[130:131]
	s_add_u32 s54, s54, s37
	s_addc_u32 s55, s55, 0
	s_add_i32 s56, s57, s39
	global_load_lds_dwordx4 v[228:229], off
	v_lshl_add_u64 v[230:231], s[54:55], 0, v[134:135]
	s_mov_b32 m0, s56
	v_lshl_add_u64 v[242:243], s[54:55], 0, v[130:131]
	global_load_lds_dwordx4 v[230:231], off
	s_add_i32 m0, s56, 0x2000
	v_lshl_add_u64 v[244:245], s[8:9], 0, v[136:137]
	global_load_lds_dwordx4 v[242:243], off
	s_mov_b32 m0, s40
	v_lshl_add_u64 v[246:247], s[8:9], 0, v[132:133]
	global_load_lds_dwordx4 v[244:245], off
	s_mov_b32 m0, s41
	s_nop 0
	global_load_lds_dwordx4 v[246:247], off
	s_waitcnt vmcnt(8)
	s_waitcnt lgkmcnt(0)
	s_barrier
	s_setprio 1
	s_waitcnt lgkmcnt(0)
	v_mfma_f32_16x16x32_bf16 v[62:65], v[148:151], v[184:187], v[62:65]
	v_mfma_f32_16x16x32_bf16 v[58:61], v[156:159], v[184:187], v[58:61]
	v_mfma_f32_16x16x32_bf16 v[46:49], v[148:151], v[192:195], v[46:49]
	v_mfma_f32_16x16x32_bf16 v[42:45], v[156:159], v[192:195], v[42:45]
	v_mfma_f32_16x16x32_bf16 v[30:33], v[148:151], v[200:203], v[30:33]
	v_mfma_f32_16x16x32_bf16 v[26:29], v[156:159], v[200:203], v[26:29]
	v_mfma_f32_16x16x32_bf16 v[14:17], v[148:151], v[208:211], v[14:17]
	v_mfma_f32_16x16x32_bf16 v[10:13], v[156:159], v[208:211], v[10:13]
	v_mfma_f32_16x16x32_bf16 v[62:65], v[152:155], v[188:191], v[62:65]
	v_mfma_f32_16x16x32_bf16 v[58:61], v[164:167], v[188:191], v[58:61]
	v_mfma_f32_16x16x32_bf16 v[46:49], v[152:155], v[196:199], v[46:49]
	v_mfma_f32_16x16x32_bf16 v[42:45], v[164:167], v[196:199], v[42:45]
	v_mfma_f32_16x16x32_bf16 v[30:33], v[152:155], v[204:207], v[30:33]
	v_mfma_f32_16x16x32_bf16 v[26:29], v[164:167], v[204:207], v[26:29]
	v_mfma_f32_16x16x32_bf16 v[14:17], v[152:155], v[212:215], v[14:17]
	v_mfma_f32_16x16x32_bf16 v[10:13], v[164:167], v[212:215], v[10:13]
	s_setprio 0
	s_setprio 1
	v_mfma_f32_16x16x32_bf16 v[54:57], v[168:171], v[184:187], v[54:57]
	v_mfma_f32_16x16x32_bf16 v[50:53], v[176:179], v[184:187], v[50:53]
	v_mfma_f32_16x16x32_bf16 v[38:41], v[168:171], v[192:195], v[38:41]
	v_mfma_f32_16x16x32_bf16 v[34:37], v[176:179], v[192:195], v[34:37]
	v_mfma_f32_16x16x32_bf16 v[22:25], v[168:171], v[200:203], v[22:25]
	v_mfma_f32_16x16x32_bf16 v[18:21], v[176:179], v[200:203], v[18:21]
	v_mfma_f32_16x16x32_bf16 v[6:9], v[168:171], v[208:211], v[6:9]
	v_mfma_f32_16x16x32_bf16 v[2:5], v[176:179], v[208:211], v[2:5]
	v_mfma_f32_16x16x32_bf16 v[54:57], v[172:175], v[188:191], v[54:57]
	v_mfma_f32_16x16x32_bf16 v[50:53], v[180:183], v[188:191], v[50:53]
	v_mfma_f32_16x16x32_bf16 v[38:41], v[172:175], v[196:199], v[38:41]
	v_mfma_f32_16x16x32_bf16 v[34:37], v[180:183], v[196:199], v[34:37]
	v_mfma_f32_16x16x32_bf16 v[22:25], v[172:175], v[204:207], v[22:25]
	v_mfma_f32_16x16x32_bf16 v[18:21], v[180:183], v[204:207], v[18:21]
	v_mfma_f32_16x16x32_bf16 v[6:9], v[172:175], v[212:215], v[6:9]
	v_mfma_f32_16x16x32_bf16 v[2:5], v[180:183], v[212:215], v[2:5]
	s_setprio 0
	s_barrier
	s_add_i32 s54, 0, 0x18000
	v_add_u32_e32 v0, s54, v141
	s_add_i32 s55, 0, 0x1c000
	ds_read_b128 v[148:151], v0
	ds_read_b128 v[152:155], v0 offset:1024
	ds_read_b128 v[156:159], v0 offset:2048
	ds_read_b128 v[164:167], v0 offset:3072
	v_add_u32_e32 v0, s55, v141
	ds_read_b128 v[168:171], v0
	ds_read_b128 v[172:175], v0 offset:1024
	ds_read_b128 v[176:179], v0 offset:2048
	ds_read_b128 v[180:183], v0 offset:3072
	s_add_u32 s8, s8, 0x40000
	s_addc_u32 s9, s9, 0
	s_mov_b32 m0, s42
	v_lshl_add_u64 v[232:233], s[8:9], 0, v[136:137]
	ds_read_b128 v[184:187], v147 offset:32768
	ds_read_b128 v[188:191], v147 offset:33792
	ds_read_b128 v[192:195], v147 offset:34816
	ds_read_b128 v[196:199], v147 offset:35840
	ds_read_b128 v[200:203], v147 offset:36864
	ds_read_b128 v[204:207], v147 offset:37888
	ds_read_b128 v[208:211], v147 offset:38912
	ds_read_b128 v[212:215], v147 offset:39936
	global_load_lds_dwordx4 v[232:233], off
	v_lshl_add_u64 v[232:233], s[8:9], 0, v[132:133]
	s_mov_b32 m0, s43
	s_nop 0
	global_load_lds_dwordx4 v[232:233], off
	s_waitcnt vmcnt(8)
	s_waitcnt lgkmcnt(0)
	s_barrier
	s_setprio 1
	s_waitcnt lgkmcnt(0)
	v_mfma_f32_16x16x32_bf16 v[126:129], v[148:151], v[184:187], v[126:129]
	v_mfma_f32_16x16x32_bf16 v[122:125], v[156:159], v[184:187], v[122:125]
	v_mfma_f32_16x16x32_bf16 v[110:113], v[148:151], v[192:195], v[110:113]
	v_mfma_f32_16x16x32_bf16 v[106:109], v[156:159], v[192:195], v[106:109]
	v_mfma_f32_16x16x32_bf16 v[94:97], v[148:151], v[200:203], v[94:97]
	v_mfma_f32_16x16x32_bf16 v[90:93], v[156:159], v[200:203], v[90:93]
	v_mfma_f32_16x16x32_bf16 v[78:81], v[148:151], v[208:211], v[78:81]
	v_mfma_f32_16x16x32_bf16 v[74:77], v[156:159], v[208:211], v[74:77]
	v_mfma_f32_16x16x32_bf16 v[126:129], v[152:155], v[188:191], v[126:129]
	v_mfma_f32_16x16x32_bf16 v[122:125], v[164:167], v[188:191], v[122:125]
	v_mfma_f32_16x16x32_bf16 v[110:113], v[152:155], v[196:199], v[110:113]
	v_mfma_f32_16x16x32_bf16 v[106:109], v[164:167], v[196:199], v[106:109]
	v_mfma_f32_16x16x32_bf16 v[94:97], v[152:155], v[204:207], v[94:97]
	v_mfma_f32_16x16x32_bf16 v[90:93], v[164:167], v[204:207], v[90:93]
	v_mfma_f32_16x16x32_bf16 v[78:81], v[152:155], v[212:215], v[78:81]
	v_mfma_f32_16x16x32_bf16 v[74:77], v[164:167], v[212:215], v[74:77]
	s_setprio 0
	s_setprio 1
	v_mfma_f32_16x16x32_bf16 v[118:121], v[168:171], v[184:187], v[118:121]
	v_mfma_f32_16x16x32_bf16 v[114:117], v[176:179], v[184:187], v[114:117]
	v_mfma_f32_16x16x32_bf16 v[102:105], v[168:171], v[192:195], v[102:105]
	v_mfma_f32_16x16x32_bf16 v[98:101], v[176:179], v[192:195], v[98:101]
	v_mfma_f32_16x16x32_bf16 v[86:89], v[168:171], v[200:203], v[86:89]
	v_mfma_f32_16x16x32_bf16 v[82:85], v[176:179], v[200:203], v[82:85]
	v_mfma_f32_16x16x32_bf16 v[70:73], v[168:171], v[208:211], v[70:73]
	v_mfma_f32_16x16x32_bf16 v[66:69], v[176:179], v[208:211], v[66:69]
	v_mfma_f32_16x16x32_bf16 v[118:121], v[172:175], v[188:191], v[118:121]
	v_mfma_f32_16x16x32_bf16 v[114:117], v[180:183], v[188:191], v[114:117]
	v_mfma_f32_16x16x32_bf16 v[102:105], v[172:175], v[196:199], v[102:105]
	v_mfma_f32_16x16x32_bf16 v[98:101], v[180:183], v[196:199], v[98:101]
	v_mfma_f32_16x16x32_bf16 v[86:89], v[172:175], v[204:207], v[86:89]
	v_mfma_f32_16x16x32_bf16 v[82:85], v[180:183], v[204:207], v[82:85]
	v_mfma_f32_16x16x32_bf16 v[70:73], v[172:175], v[212:215], v[70:73]
	v_mfma_f32_16x16x32_bf16 v[66:69], v[180:183], v[212:215], v[66:69]
	s_setprio 0
	s_barrier
	s_add_i32 s8, s54, s39
	v_lshl_add_u64 v[226:227], v[226:227], 0, s[94:95]
	s_mov_b32 m0, s8
	ds_read_b128 v[184:187], v147 offset:49152
	ds_read_b128 v[188:191], v147 offset:50176
	ds_read_b128 v[192:195], v147 offset:51200
	ds_read_b128 v[196:199], v147 offset:52224
	ds_read_b128 v[200:203], v147 offset:53248
	ds_read_b128 v[204:207], v147 offset:54272
	ds_read_b128 v[208:211], v147 offset:55296
	ds_read_b128 v[212:215], v147 offset:56320
	global_load_lds_dwordx4 v[226:227], off
	v_lshl_add_u64 v[226:227], v[228:229], 0, s[94:95]
	s_add_i32 m0, s8, 0x2000
	s_add_i32 s8, s55, s39
	global_load_lds_dwordx4 v[226:227], off
	v_lshl_add_u64 v[226:227], v[230:231], 0, s[94:95]
	s_mov_b32 m0, s8
	s_nop 0
	global_load_lds_dwordx4 v[226:227], off
	v_lshl_add_u64 v[226:227], v[242:243], 0, s[94:95]
	s_add_i32 m0, s8, 0x2000
	s_nop 0
	global_load_lds_dwordx4 v[226:227], off
	v_lshl_add_u64 v[226:227], v[244:245], 0, s[94:95]
	s_mov_b32 m0, s44
	s_nop 0
	global_load_lds_dwordx4 v[226:227], off
	v_lshl_add_u64 v[226:227], v[246:247], 0, s[94:95]
	s_mov_b32 m0, s45
	s_nop 0
	global_load_lds_dwordx4 v[226:227], off
	s_waitcnt vmcnt(8)
	s_waitcnt lgkmcnt(0)
	s_barrier
	s_setprio 1
	s_waitcnt lgkmcnt(0)
	v_mfma_f32_16x16x32_bf16 v[62:65], v[148:151], v[184:187], v[62:65]
	v_mfma_f32_16x16x32_bf16 v[58:61], v[156:159], v[184:187], v[58:61]
	v_mfma_f32_16x16x32_bf16 v[46:49], v[148:151], v[192:195], v[46:49]
	v_mfma_f32_16x16x32_bf16 v[42:45], v[156:159], v[192:195], v[42:45]
	v_mfma_f32_16x16x32_bf16 v[30:33], v[148:151], v[200:203], v[30:33]
	v_mfma_f32_16x16x32_bf16 v[26:29], v[156:159], v[200:203], v[26:29]
	v_mfma_f32_16x16x32_bf16 v[14:17], v[148:151], v[208:211], v[14:17]
	v_mfma_f32_16x16x32_bf16 v[10:13], v[156:159], v[208:211], v[10:13]
	v_mfma_f32_16x16x32_bf16 v[62:65], v[152:155], v[188:191], v[62:65]
	v_mfma_f32_16x16x32_bf16 v[58:61], v[164:167], v[188:191], v[58:61]
	v_mfma_f32_16x16x32_bf16 v[46:49], v[152:155], v[196:199], v[46:49]
	v_mfma_f32_16x16x32_bf16 v[42:45], v[164:167], v[196:199], v[42:45]
	v_mfma_f32_16x16x32_bf16 v[30:33], v[152:155], v[204:207], v[30:33]
	v_mfma_f32_16x16x32_bf16 v[26:29], v[164:167], v[204:207], v[26:29]
	v_mfma_f32_16x16x32_bf16 v[14:17], v[152:155], v[212:215], v[14:17]
	v_mfma_f32_16x16x32_bf16 v[10:13], v[164:167], v[212:215], v[10:13]
	s_setprio 0
	s_setprio 1
	v_mfma_f32_16x16x32_bf16 v[54:57], v[168:171], v[184:187], v[54:57]
	v_mfma_f32_16x16x32_bf16 v[50:53], v[176:179], v[184:187], v[50:53]
	v_mfma_f32_16x16x32_bf16 v[38:41], v[168:171], v[192:195], v[38:41]
	v_mfma_f32_16x16x32_bf16 v[34:37], v[176:179], v[192:195], v[34:37]
	v_mfma_f32_16x16x32_bf16 v[22:25], v[168:171], v[200:203], v[22:25]
	v_mfma_f32_16x16x32_bf16 v[18:21], v[176:179], v[200:203], v[18:21]
	v_mfma_f32_16x16x32_bf16 v[6:9], v[168:171], v[208:211], v[6:9]
	v_mfma_f32_16x16x32_bf16 v[2:5], v[176:179], v[208:211], v[2:5]
	v_mfma_f32_16x16x32_bf16 v[54:57], v[172:175], v[188:191], v[54:57]
	v_mfma_f32_16x16x32_bf16 v[50:53], v[180:183], v[188:191], v[50:53]
	v_mfma_f32_16x16x32_bf16 v[38:41], v[172:175], v[196:199], v[38:41]
	v_mfma_f32_16x16x32_bf16 v[34:37], v[180:183], v[196:199], v[34:37]
	v_mfma_f32_16x16x32_bf16 v[22:25], v[172:175], v[204:207], v[22:25]
	v_mfma_f32_16x16x32_bf16 v[18:21], v[180:183], v[204:207], v[18:21]
	v_mfma_f32_16x16x32_bf16 v[6:9], v[172:175], v[212:215], v[6:9]
	v_mfma_f32_16x16x32_bf16 v[2:5], v[180:183], v[212:215], v[2:5]
	s_setprio 0
	s_barrier
	s_add_u32 s0, s0, 0x100
	s_addc_u32 s1, s1, 0
	s_add_u32 s34, s34, 0x100
	s_addc_u32 s35, s35, 0
	s_cmp_ge_u32 s53, s5
	s_mov_b32 s8, s53
	s_cbranch_scc0 .LBB0_402
	s_and_b64 vcc, exec, s[20:21]
	s_cbranch_vccz .LBB0_405
	s_barrier
.LBB0_405:
	s_and_b64 vcc, exec, s[2:3]
	s_cbranch_vccz .Lfuse_no
	s_cmp_lt_u32 s4, 3
	s_cbranch_scc1 .Lfuse_rescale

.Lfuse_rescale:
	v_lshl_add_u32 v176, s51, 8, v139
	v_ashrrev_i32_e32 v177, 31, v176
	v_lshl_add_u64 v[178:179], v[176:177], 4, s[24:25]
	global_load_dword v190, v[178:179], off
	global_load_dword v198, v[178:179], off offset:4
	global_load_dword v191, v[178:179], off offset:256
	global_load_dword v199, v[178:179], off offset:260
	global_load_dword v192, v[178:179], off offset:512
	global_load_dword v200, v[178:179], off offset:516
	global_load_dword v193, v[178:179], off offset:768
	global_load_dword v201, v[178:179], off offset:772
	global_load_dword v194, v[178:179], off offset:2048
	global_load_dword v202, v[178:179], off offset:2052
	global_load_dword v195, v[178:179], off offset:2304
	global_load_dword v203, v[178:179], off offset:2308
	global_load_dword v196, v[178:179], off offset:2560
	global_load_dword v204, v[178:179], off offset:2564
	global_load_dword v197, v[178:179], off offset:2816
	global_load_dword v205, v[178:179], off offset:2820
	s_waitcnt vmcnt(0)
	v_fmamk_f32 v180, v190, 0x3b000000, v219
	v_fmamk_f32 v181, v198, 0x3b000000, v219
	v_rsq_f32_e32 v180, v180
	v_sqrt_f32_e32 v181, v181
	s_nop 0
	v_mul_f32_e32 v174, v180, v181
	v_fmamk_f32 v180, v191, 0x3b000000, v219
	v_fmamk_f32 v181, v199, 0x3b000000, v219
	v_rsq_f32_e32 v180, v180
	v_sqrt_f32_e32 v181, v181
	s_nop 0
	v_mul_f32_e32 v170, v180, v181
	v_fmamk_f32 v180, v192, 0x3b000000, v219
	v_fmamk_f32 v181, v200, 0x3b000000, v219
	v_rsq_f32_e32 v180, v180
	v_sqrt_f32_e32 v181, v181
	s_nop 0
	v_mul_f32_e32 v166, v180, v181
	v_fmamk_f32 v180, v193, 0x3b000000, v219
	v_fmamk_f32 v181, v201, 0x3b000000, v219
	v_rsq_f32_e32 v180, v180
	v_sqrt_f32_e32 v181, v181
	s_nop 0
	v_mul_f32_e32 v158, v180, v181
	v_fmamk_f32 v180, v194, 0x3b000000, v219
	v_fmamk_f32 v181, v202, 0x3b000000, v219
	v_rsq_f32_e32 v180, v180
	v_sqrt_f32_e32 v181, v181
	s_nop 0
	v_mul_f32_e32 v156, v180, v181
	v_fmamk_f32 v180, v195, 0x3b000000, v219
	v_fmamk_f32 v181, v203, 0x3b000000, v219
	v_rsq_f32_e32 v180, v180
	v_sqrt_f32_e32 v181, v181
	s_nop 0
	v_mul_f32_e32 v152, v180, v181
	v_fmamk_f32 v180, v196, 0x3b000000, v219
	v_fmamk_f32 v181, v204, 0x3b000000, v219
	v_rsq_f32_e32 v180, v180
	v_sqrt_f32_e32 v181, v181
	s_nop 0
	v_mul_f32_e32 v148, v180, v181
	v_fmamk_f32 v180, v197, 0x3b000000, v219
	v_fmamk_f32 v181, v205, 0x3b000000, v219
	v_rsq_f32_e32 v180, v180
	v_sqrt_f32_e32 v181, v181
	s_nop 0
	v_mul_f32_e32 v146, v180, v181
	v_pk_mul_f32 v[128:129], v[128:129], v[174:175] op_sel_hi:[1,0]
	v_pk_mul_f32 v[126:127], v[126:127], v[174:175] op_sel_hi:[1,0]
	v_pk_mul_f32 v[124:125], v[124:125], v[174:175] op_sel_hi:[1,0]
	v_pk_mul_f32 v[122:123], v[122:123], v[174:175] op_sel_hi:[1,0]
	v_pk_mul_f32 v[120:121], v[120:121], v[174:175] op_sel_hi:[1,0]
	v_pk_mul_f32 v[118:119], v[118:119], v[174:175] op_sel_hi:[1,0]
	v_pk_mul_f32 v[116:117], v[116:117], v[174:175] op_sel_hi:[1,0]
	v_pk_mul_f32 v[114:115], v[114:115], v[174:175] op_sel_hi:[1,0]
	v_pk_mul_f32 v[112:113], v[112:113], v[170:171] op_sel_hi:[1,0]
	v_pk_mul_f32 v[110:111], v[110:111], v[170:171] op_sel_hi:[1,0]
	v_pk_mul_f32 v[108:109], v[108:109], v[170:171] op_sel_hi:[1,0]
	v_pk_mul_f32 v[106:107], v[106:107], v[170:171] op_sel_hi:[1,0]
	v_pk_mul_f32 v[104:105], v[104:105], v[170:171] op_sel_hi:[1,0]
	v_pk_mul_f32 v[102:103], v[102:103], v[170:171] op_sel_hi:[1,0]
	v_pk_mul_f32 v[100:101], v[100:101], v[170:171] op_sel_hi:[1,0]
	v_pk_mul_f32 v[98:99], v[98:99], v[170:171] op_sel_hi:[1,0]
	v_pk_mul_f32 v[96:97], v[96:97], v[166:167] op_sel_hi:[1,0]
	v_pk_mul_f32 v[94:95], v[94:95], v[166:167] op_sel_hi:[1,0]
	v_pk_mul_f32 v[92:93], v[92:93], v[166:167] op_sel_hi:[1,0]
	v_pk_mul_f32 v[90:91], v[90:91], v[166:167] op_sel_hi:[1,0]
	v_pk_mul_f32 v[88:89], v[88:89], v[166:167] op_sel_hi:[1,0]
	v_pk_mul_f32 v[86:87], v[86:87], v[166:167] op_sel_hi:[1,0]
	v_pk_mul_f32 v[84:85], v[84:85], v[166:167] op_sel_hi:[1,0]
	v_pk_mul_f32 v[82:83], v[82:83], v[166:167] op_sel_hi:[1,0]
	v_pk_mul_f32 v[80:81], v[80:81], v[158:159] op_sel_hi:[1,0]
	v_pk_mul_f32 v[78:79], v[78:79], v[158:159] op_sel_hi:[1,0]
	v_pk_mul_f32 v[76:77], v[76:77], v[158:159] op_sel_hi:[1,0]
	v_pk_mul_f32 v[74:75], v[74:75], v[158:159] op_sel_hi:[1,0]
	v_pk_mul_f32 v[72:73], v[72:73], v[158:159] op_sel_hi:[1,0]
	v_pk_mul_f32 v[70:71], v[70:71], v[158:159] op_sel_hi:[1,0]
	v_pk_mul_f32 v[68:69], v[68:69], v[158:159] op_sel_hi:[1,0]
	v_pk_mul_f32 v[66:67], v[66:67], v[158:159] op_sel_hi:[1,0]
	v_pk_mul_f32 v[64:65], v[64:65], v[156:157] op_sel_hi:[1,0]
	v_pk_mul_f32 v[62:63], v[62:63], v[156:157] op_sel_hi:[1,0]
	v_pk_mul_f32 v[60:61], v[60:61], v[156:157] op_sel_hi:[1,0]
	v_pk_mul_f32 v[58:59], v[58:59], v[156:157] op_sel_hi:[1,0]
	v_pk_mul_f32 v[56:57], v[56:57], v[156:157] op_sel_hi:[1,0]
	v_pk_mul_f32 v[54:55], v[54:55], v[156:157] op_sel_hi:[1,0]
	v_pk_mul_f32 v[52:53], v[52:53], v[156:157] op_sel_hi:[1,0]
	v_pk_mul_f32 v[50:51], v[50:51], v[156:157] op_sel_hi:[1,0]
	v_pk_mul_f32 v[48:49], v[48:49], v[152:153] op_sel_hi:[1,0]
	v_pk_mul_f32 v[46:47], v[46:47], v[152:153] op_sel_hi:[1,0]
	v_pk_mul_f32 v[44:45], v[44:45], v[152:153] op_sel_hi:[1,0]
	v_pk_mul_f32 v[42:43], v[42:43], v[152:153] op_sel_hi:[1,0]
	v_pk_mul_f32 v[40:41], v[40:41], v[152:153] op_sel_hi:[1,0]
	v_pk_mul_f32 v[38:39], v[38:39], v[152:153] op_sel_hi:[1,0]
	v_pk_mul_f32 v[36:37], v[36:37], v[152:153] op_sel_hi:[1,0]
	v_pk_mul_f32 v[34:35], v[34:35], v[152:153] op_sel_hi:[1,0]
	v_pk_mul_f32 v[32:33], v[32:33], v[148:149] op_sel_hi:[1,0]
	v_pk_mul_f32 v[30:31], v[30:31], v[148:149] op_sel_hi:[1,0]
	v_pk_mul_f32 v[28:29], v[28:29], v[148:149] op_sel_hi:[1,0]
	v_pk_mul_f32 v[26:27], v[26:27], v[148:149] op_sel_hi:[1,0]
	v_pk_mul_f32 v[24:25], v[24:25], v[148:149] op_sel_hi:[1,0]
	v_pk_mul_f32 v[22:23], v[22:23], v[148:149] op_sel_hi:[1,0]
	v_pk_mul_f32 v[20:21], v[20:21], v[148:149] op_sel_hi:[1,0]
	v_pk_mul_f32 v[18:19], v[18:19], v[148:149] op_sel_hi:[1,0]
	v_pk_mul_f32 v[16:17], v[16:17], v[146:147] op_sel_hi:[1,0]
	v_pk_mul_f32 v[14:15], v[14:15], v[146:147] op_sel_hi:[1,0]
	v_pk_mul_f32 v[12:13], v[12:13], v[146:147] op_sel_hi:[1,0]
	v_pk_mul_f32 v[10:11], v[10:11], v[146:147] op_sel_hi:[1,0]
	v_pk_mul_f32 v[8:9], v[8:9], v[146:147] op_sel_hi:[1,0]
	v_pk_mul_f32 v[6:7], v[6:7], v[146:147] op_sel_hi:[1,0]
	v_pk_mul_f32 v[4:5], v[4:5], v[146:147] op_sel_hi:[1,0]
	v_pk_mul_f32 v[2:3], v[2:3], v[146:147] op_sel_hi:[1,0]
	v_mov_b32_e32 v206, v2
	v_mov_b32_e32 v207, v3
	v_mov_b32_e32 v208, v4
	v_mov_b32_e32 v209, v5
	v_mov_b32_e32 v210, v6
	v_mov_b32_e32 v211, v7
	v_mov_b32_e32 v212, v8
	v_mov_b32_e32 v213, v9
	v_mov_b32_e32 v214, v10
	v_mov_b32_e32 v215, v11
	v_mov_b32_e32 v226, v12
	v_mov_b32_e32 v227, v13
	v_mov_b32_e32 v228, v14
	v_mov_b32_e32 v229, v15
	v_mov_b32_e32 v230, v16
	v_mov_b32_e32 v231, v17
	v_mov_b32_e32 v232, v18
	v_mov_b32_e32 v233, v19
	s_and_b64 vcc, exec, s[6:7]
	s_mov_b64 s[0:1], -1
	s_cbranch_vccnz .LBB0_392
	s_andn2_b64 vcc, exec, s[18:19]
	s_cbranch_vccnz .LBB0_391
	s_barrier
	s_branch .LBB0_391
